# combo10 + odd XCDs start the GLU GEMM 6 us late
# baseline (speedup 1.0000x reference)
.LBB0_705:
	s_or_b64 exec, exec, s[0:1]
	s_and_b32 s3, s93, 0x60
	s_lshl_b32 s33, s3, 7
	s_cmpk_lt_i32 s97, 0x200
	v_mov_b32_e32 v8, v234
	s_cselect_b64 s[4:5], -1, 0
	s_cmpk_gt_i32 s97, 0x1ff
	s_barrier
	s_bfe_u32 s99, s97, 0x10000
	s_cmp_eq_u32 s99, 0
	s_cbranch_scc1 .Lmy_p3_nodelay
	s_mul_i32 s99, s99, 600
	s_memrealtime s[100:101]
	s_waitcnt lgkmcnt(0)
	s_add_u32 s98, s100, s99

.Lmy_p3_nodelay:
	s_cmpk_gt_i32 s97, 0x1ff
	s_cbranch_scc1 .LBB0_730
	s_ashr_i32 s18, s97, 31
	s_lshr_b32 s0, s18, 29
	s_add_i32 s8, s97, s0
	s_and_b32 s0, s8, -8
	s_sub_i32 s9, s97, s0
	s_cmp_gt_i32 s9, -1
	s_cbranch_scc0 .LBB0_708
	s_lshl_b32 s2, s9, 6
	s_mov_b64 s[0:1], 0
	s_branch .LBB0_709
